# scan workgroups also take latent attention units after their chain; scan loop fragment prefetch; per-XCD queues
# baseline (speedup 1.0000x reference)
.LBB0_367:
	s_or_b64 exec, exec, s[4:5]
	s_and_b32 s2, s65, 1
	s_lshr_b32 s1, s65, 1
	s_add_i32 s0, s2, 1
	s_ashr_i32 s33, s3, 31
	s_ashr_i32 s78, s65, 31
	s_ashr_i32 s8, s65, 1
	s_cmpk_gt_i32 s65, 0x7f
	s_cselect_b64 s[4:5], -1, 0
	v_writelane_b32 v254, s0, 6
	s_and_b64 s[4:5], s[4:5], s[6:7]
	v_writelane_b32 v254, s4, 7
	s_mov_b32 s75, 0
	s_mov_b32 s15, s75
	v_writelane_b32 v254, s5, 8
	s_movk_i32 s92, 0x2c00
	v_readlane_b32 s11, v254, 2
	s_add_i32 s0, s11, 0xfffffc00
	s_cmpk_lt_i32 s65, 0x200
	s_cselect_b64 s[4:5], -1, 0
	s_lshr_b32 s2, s78, 29
	s_add_i32 s2, s65, s2
	s_ashr_i32 s9, s2, 3
	s_and_b32 s2, s2, -8
	s_sub_i32 s2, s65, s2
	v_writelane_b32 v254, s0, 9
	s_lshl_b32 s10, s2, 6
	v_writelane_b32 v254, s4, 10
	s_cmpk_gt_i32 s65, 0x9f
	v_mov_b32_e32 v1, 0
	v_writelane_b32 v254, s5, 11
	s_cselect_b64 s[4:5], -1, 0
	s_and_b64 s[4:5], s[4:5], s[6:7]
	v_writelane_b32 v254, s4, 12
	s_add_i32 s0, s11, 0xfffffb00
	s_cmpk_lt_i32 s65, 0x300
	v_writelane_b32 v254, s5, 13
	v_writelane_b32 v254, s0, 14
	s_cselect_b64 s[4:5], -1, 0
	s_lshl_b32 s12, s3, 4
	v_writelane_b32 v254, s4, 15
	s_cmpk_gt_i32 s65, 0x8f
	s_movk_i32 s93, 0x1000
	v_writelane_b32 v254, s5, 16
	s_cselect_b64 s[4:5], -1, 0
	v_writelane_b32 v254, s4, 17
	s_cmp_gt_i32 s65, -1
	s_movk_i32 s64, 0x2000
	v_writelane_b32 v254, s5, 18
	s_cselect_b64 s[4:5], -1, 0
	s_cmp_lt_i32 s3, 32
	s_cselect_b64 s[6:7], -1, 0
	s_or_b64 s[4:5], s[4:5], s[6:7]
	s_cmp_lt_i32 s2, 0
	s_mulk_i32 s2, 0x41
	s_cselect_b32 s2, s2, s10
	v_writelane_b32 v254, s4, 19
	s_add_i32 s2, s2, s9
	s_abs_i32 s9, s3
	v_writelane_b32 v254, s5, 20
	s_ashr_i32 s4, s2, 31
	s_lshr_b32 s4, s4, 26
	s_add_i32 s4, s2, s4
	s_ashr_i32 s5, s4, 6
	s_and_b32 s4, s4, 0xffc0
	s_sub_i32 s4, s2, s4
	s_bfe_i32 s2, s4, 0x80000
	s_bfe_u32 s2, s2, 0x3000c
	s_add_i32 s6, s4, s2
	s_waitcnt lgkmcnt(0)
	v_cvt_f32_u32_e32 v0, s9
	s_bfe_i32 s2, s6, 0x80000
	s_and_b32 s6, s6, 0xf8
	s_sub_i32 s4, s4, s6
	s_lshl_b32 s5, s5, 3
	s_sext_i32_i8 s4, s4
	s_add_i32 s0, s5, s4
	v_rcp_iflag_f32_e32 v0, v0
	s_mul_hi_i32 s4, s0, 0x210000
	s_sext_i32_i16 s7, s2
	v_writelane_b32 v254, s4, 21
	s_ashr_i32 s6, s7, 3
	v_writelane_b32 v254, s0, 22
	s_mul_i32 s0, s0, 0x210000
	v_writelane_b32 v254, s0, 23
	s_mul_hi_i32 s0, s6, 0x2c0000
	v_mul_f32_e32 v0, 0x4f7ffffe, v0
	s_lshr_b32 s2, s7, 3
	v_writelane_b32 v254, s0, 24
	v_cvt_u32_f32_e32 v0, v0
	s_bfe_i64 s[4:5], s[2:3], 0x100000
	v_writelane_b32 v254, s6, 25
	s_mul_i32 s0, s6, 0x2c0000
	v_writelane_b32 v254, s0, 26
	s_lshl_b64 s[4:5], s[4:5], 20
	v_writelane_b32 v254, s4, 27
	s_sub_i32 s2, 0, s9
	s_movk_i32 s96, 0x4800
	v_writelane_b32 v254, s5, 28
	v_readfirstlane_b32 s4, v0
	s_mul_i32 s2, s2, s4
	s_mul_hi_u32 s2, s4, s2
	s_add_i32 s2, s4, s2
	s_mul_hi_u32 s4, s2, 0x840
	s_mul_i32 s4, s4, s9
	s_sub_i32 s4, 0x840, s4
	s_sub_i32 s5, s4, s9
	s_cmp_ge_u32 s4, s9
	s_cselect_b32 s4, s5, s4
	s_sub_i32 s5, s4, s9
	s_cmp_ge_u32 s4, s9
	s_cselect_b32 s6, s5, s4
	s_sub_i32 s14, 0x840, s6
	s_cmp_eq_u32 s6, 0
	s_cselect_b64 s[4:5], -1, 0
	s_lshl_b32 s6, s6, 1
	s_cmp_gt_i32 s6, s3
	s_cselect_b64 s[6:7], -1, 0
	s_or_b64 s[6:7], s[4:5], s[6:7]
	s_cmp_lt_i32 s65, s14
	s_cselect_b64 s[4:5], -1, 0
	v_writelane_b32 v254, s6, 29
	s_or_b64 s[4:5], s[6:7], s[4:5]
	s_add_i32 s16, s14, s3
	v_writelane_b32 v254, s7, 30
	v_writelane_b32 v254, s4, 31
	s_mul_hi_u32 s2, s2, 0x450
	s_mul_i32 s2, s2, s9
	v_writelane_b32 v254, s5, 32
	s_xor_b64 s[4:5], s[4:5], -1
	v_writelane_b32 v254, s4, 33
	s_cmp_lt_u32 s65, s16
	v_mov_b32_e32 v226, 0x358637bd
	v_writelane_b32 v254, s5, 34
	s_cselect_b64 s[4:5], -1, 0
	v_writelane_b32 v254, s4, 35
	s_add_i32 s0, s14, s1
	s_sub_i32 s2, 0x450, s2
	v_writelane_b32 v254, s5, 36
	v_writelane_b32 v254, s0, 37
	v_writelane_b32 v254, s14, 38
	s_add_i32 s4, s14, s8
	s_ashr_i32 s5, s4, 31
	v_writelane_b32 v254, s15, 39
	v_writelane_b32 v254, s4, 40
	s_ashr_i32 s17, s16, 31
	s_movk_i32 s84, 0x7fff
	v_writelane_b32 v254, s5, 41
	s_sub_i32 s4, s2, s9
	s_cmp_ge_u32 s2, s9
	s_cselect_b32 s2, s4, s2
	s_sub_i32 s4, s2, s9
	s_cmp_ge_u32 s2, s9
	s_cselect_b32 s2, s4, s2
	s_sub_i32 s0, 0x450, s2
	s_cmp_eq_u32 s2, 0
	s_cselect_b64 s[4:5], -1, 0
	s_lshl_b32 s2, s2, 1
	s_cmp_gt_i32 s2, s3
	s_cselect_b64 s[6:7], -1, 0
	s_or_b64 s[6:7], s[4:5], s[6:7]
	s_cmp_lt_i32 s65, s0
	s_cselect_b64 s[4:5], -1, 0
	v_writelane_b32 v254, s6, 42
	s_or_b64 s[4:5], s[6:7], s[4:5]
	s_mov_b32 s85, 0xffff0000
	v_writelane_b32 v254, s7, 43
	v_writelane_b32 v254, s4, 44
	v_mov_b32_e32 v231, 0x16000
	v_mov_b64_e32 v[198:199], 0x200
	v_writelane_b32 v254, s5, 45
	s_xor_b64 s[4:5], s[4:5], -1
	v_writelane_b32 v254, s4, 46
	v_mov_b64_e32 v[200:201], 0x1ff
	v_mov_b32_e32 v246, 0x81f0
	v_writelane_b32 v254, s5, 47
	s_add_i32 s4, s0, s3
	s_cmp_lt_u32 s65, s4
	s_cselect_b64 s[6:7], -1, 0
	v_writelane_b32 v254, s6, 48
	s_add_i32 s1, s0, s1
	s_ashr_i32 s5, s4, 31
	v_writelane_b32 v254, s7, 49
	v_writelane_b32 v254, s1, 50
	v_writelane_b32 v254, s4, 51
	s_mov_b32 s1, s75
	v_mov_b32_e32 v247, 0x7fe0
	v_writelane_b32 v254, s5, 52
	v_writelane_b32 v254, s0, 53
	v_mov_b32_e32 v248, 0x2d60
	v_mov_b32_e32 v249, 0x5280
	v_writelane_b32 v254, s1, 54
	s_add_i32 s0, s0, s8
	s_ashr_i32 s1, s0, 31
	v_writelane_b32 v254, s0, 55
	v_mov_b32_e32 v250, 0x2f70
	v_mov_b32_e32 v251, 0x5070
	v_writelane_b32 v254, s1, 56
	v_writelane_b32 v254, s16, 57
	s_cmp_lt_i32 s65, s16
	s_cselect_b64 s[0:1], -1, 0
	v_writelane_b32 v254, s17, 58
	v_writelane_b32 v254, s0, 59
	s_ashr_i32 s47, s46, 31
	s_lshl_b64 s[72:73], s[46:47], 11
	v_writelane_b32 v254, s1, 60
	s_add_i32 s0, s11, 0xffffa300
	v_writelane_b32 v254, s0, 61
	s_add_i32 s0, s11, 0xffff7000
	v_writelane_b32 v254, s0, 62
	s_lshl_b32 s0, s97, 3
	s_and_b32 s0, s0, 0xfffffe00
	v_writelane_b32 v254, s0, 63
	s_ashr_i32 s0, s12, 31
	v_writelane_b32 v255, s0, 0
	s_mul_i32 s0, s3, 0x2c000
	v_writelane_b32 v255, s12, 1
	s_mul_hi_i32 s1, s12, 0x2c00
	v_writelane_b32 v255, s0, 2
	s_lshl_b32 s16, s3, 9
	s_lshl_b64 s[88:89], s[46:47], 12
	v_writelane_b32 v255, s1, 3
	s_add_i32 s0, s11, 0xfffff780
	v_writelane_b32 v255, s0, 4
	s_mul_hi_i32 s1, s46, 0x2c00
	s_mul_i32 s0, s46, 0x2c00
	v_writelane_b32 v255, s0, 5
	s_mov_b32 s97, 0x800000
	v_mov_b32_e32 v252, 0x3180
	v_writelane_b32 v255, s1, 6
	s_add_i32 s0, s11, 0xffff7100
	v_writelane_b32 v255, s0, 7
	v_writelane_b32 v255, s90, 8
	v_writelane_b32 v255, s72, 9
	v_mov_b32_e32 v253, 0x4e60
	v_mov_b32_e32 v229, 0x3390
	v_writelane_b32 v255, s73, 10
	v_mov_b32_e32 v227, 0x4c50
	v_mov_b32_e32 v228, 0x35a0
	v_mov_b32_e32 v196, 0x4a40
	v_mov_b32_e32 v197, 0x37b0
	v_mov_b32_e32 v230, 0x4830
	v_mov_b32_e32 v232, 0x39c0
	v_mov_b32_e32 v233, 0x4620
	v_mov_b32_e32 v234, 0x3bd0
	v_mov_b32_e32 v235, 0x4410
	v_mov_b32_e32 v236, 0x3de0
	v_mov_b32_e32 v237, 0x4200
	v_mov_b32_e32 v238, 0x3ff0
	v_mov_b32_e32 v239, 0x7fc00000
	s_movk_i32 s1, 0x4000
	s_mov_b32 s81, 0xc000
	s_movk_i32 s79, 0x210
	s_mov_b64 s[82:83], 0x160000
	s_mov_b64 s[44:45], 0x80
	s_mov_b64 s[62:63], 0x80000
	s_mov_b64 s[6:7], -1
	s_lshl_b64 s[68:69], s[46:47], 13
	s_mov_b32 s60, s75
	s_mov_b32 s48, 0x3f803f80
	s_mov_b64 s[86:87], s[88:89]
	v_writelane_b32 v255, s16, 11
	s_barrier
	s_branch .LBB0_370
